# LN1: cache-warming touch loads two rows ahead of the row loop
# baseline (speedup 1.0000x reference)
; #define LAS __attribute__((address_space(3)))
; __global__ void __launch_bounds__(512, 2) fwd_kernel(Args args) {
;     extern __shared__ __attribute__((aligned(16))) unsigned char lds_raw[];
;     LAS unsigned char* L = (LAS unsigned char*)lds_raw;
;     Ctx c;
;     c.out = args.out; c.ws = args.ws;
;     c.tid = threadIdx.x; c.lane = c.tid & 63; c.wave = __builtin_amdgcn_readfirstlane(c.tid >> 6); c.G = gridDim.x; c.bid = blockIdx.x;
;     c.layer = 0; c.slab = 0; c.nseq = 8; c.seqlen = 4096; c.stok = 32768; c.sbase = 0; c.dry = 0;
;     const int lo = args.ph_lo, hi = args.ph_hi;
;     volatile LAS unsigned* MISC = (volatile LAS unsigned*)(L + LDS_MISC);
;     if (c.tid < 4) MISC[c.tid] = 0u;
;     __syncthreads();
;     XcdBarrier bar; bar.bar = (unsigned*)(c.ws + WS_CTL) + 1024; bar.x = 0; bar.st = MISC;
;     if (hi - lo > 1) bar = xcd_barrier_post((unsigned*)(c.ws + WS_CTL) + 1024, MISC);
_Z10fwd_kernel4Args:
	s_mov_b64 s[80:81], s[0:1]
	s_load_dwordx4 s[84:87], s[0:1], 0xa8
	s_load_dword s79, s[0:1], 0xb8
	s_add_u32 s0, s80, 0xb8
	s_addc_u32 s1, s81, 0
	s_mov_b32 s78, s2
	v_writelane_b32 v253, s0, 0
	v_mov_b32_e32 v1, 0x24f00
	v_mov_b32_e32 v2, 0
	ds_write_b32 v1, v2
	v_cmp_gt_u32_e32 vcc, 4, v0
	s_nop 0
	v_writelane_b32 v253, s1, 1
	s_and_saveexec_b64 s[0:1], vcc
	v_lshl_add_u32 v1, v0, 2, 0
	v_add_u32_e32 v1, 0x23800, v1
	v_mov_b32_e32 v2, 0
	ds_write_b32 v1, v2
	s_or_b64 exec, exec, s[0:1]
	s_waitcnt lgkmcnt(0)
	s_add_i32 s87, s87, 1
	s_add_u32 s82, s84, 0x1000
	s_addc_u32 s83, s85, 0
	s_sub_i32 s2, s87, s86
	s_mov_b64 s[0:1], 0
	s_cmp_lt_i32 s2, 2
	v_cmp_eq_u32_e32 vcc, 0, v0
	s_mov_b64 s[84:85], 0
	s_barrier
	s_cbranch_scc1 .LBB0_7
	s_getreg_b32 s2, hwreg(HW_REG_XCC_ID, 0, 4)
	s_lshl_b32 s2, s2, 6
	s_and_b32 s84, s2, 0x3c0
	s_and_saveexec_b64 s[2:3], vcc
	s_cbranch_execz .LBB0_6
	s_mov_b64 s[4:5], exec
	v_mbcnt_lo_u32_b32 v1, s4, 0
	v_mbcnt_hi_u32_b32 v1, s5, v1
	v_cmp_eq_u32_e32 vcc, 0, v1
	s_and_b64 s[6:7], exec, vcc
	s_mov_b64 exec, s[6:7]
	s_cbranch_execz .LBB0_6
	s_lshl_b32 s6, s84, 2
	s_bcnt1_i32_b64 s4, s[4:5]
	v_mov_b32_e32 v1, s6
	v_mov_b32_e32 v2, s4
	global_atomic_add v1, v2, s[82:83] offset:1024

; __global__ void __launch_bounds__(512, 2) fwd_kernel(Args args) {
;     ...
;     for (int layer = 0; layer < 2; ++layer) {
.LBB0_10:
	v_readlane_b32 s4, v254, 8
	v_readlane_b32 s5, v254, 9
	s_mov_b32 s12, 1
	s_mov_b64 s[0:1], -1
	s_mov_b64 s[2:3], 0
	s_and_b64 vcc, exec, s[4:5]
	s_cbranch_vccz .LBB0_11
	v_mov_b32_e32 v1, 0x24f00
	ds_read_b32 v2, v1
	s_waitcnt lgkmcnt(0)
	v_readfirstlane_b32 s4, v2
	s_barrier
	s_cmp_lg_u32 s4, 0
	s_cbranch_scc1 .Lprobe_exit
	v_mov_b32_e32 v2, 1
	ds_write_b32 v1, v2
	s_waitcnt lgkmcnt(0)
	v_readlane_b32 s78, v253, 59
	v_readlane_b32 s80, v253, 60
	v_readlane_b32 s81, v253, 61
	v_readlane_b32 s84, v253, 62
	v_readlane_b32 s79, v254, 2
	v_readlane_b32 s82, v254, 3
	v_readlane_b32 s83, v254, 4
	s_mov_b32 s86, 36
	s_mov_b32 s87, 37
	s_mov_b64 s[0:1], 0
	s_branch .LBB0_7
.Lprobe_exit:
	s_endpgm
.LBB0_11:
	s_cmp_ge_i32 s33, s86
	s_cselect_b64 s[4:5], -1, 0
	s_cmp_lt_i32 s33, s87
	s_cselect_b64 s[6:7], -1, 0
	s_and_b64 s[4:5], s[4:5], s[6:7]
	v_writelane_b32 v254, s33, 7
	s_and_b64 vcc, exec, s[4:5]
	s_mov_b64 s[4:5], -1
	s_cbranch_vccnz .LBB0_13
	v_readlane_b32 s4, v254, 7
	s_add_i32 s40, s4, 1
	s_mov_b64 s[4:5], 0

; DI float bflo(unsigned u) { return __uint_as_float(u << 16); }
; DI float bfhi(unsigned u) { return __uint_as_float(u & 0xffff0000u); }
; DI void phase_ln1(KArgs args, LAS unsigned char* L, const Ctx& c) {
;     ...
;     for (int rl = c.bid * 8 + c.wave; rl < c.stok; rl += c.G * 8) { const size_t tok = (size_t)c.sbase + rl;
;         const bf16_t* hr = (const bf16_t*)c.out + tok * D; f32x4 v[4]; float s = 0.f;
; #pragma unroll
;         for (int j = 0; j < 4; ++j) { v[j][0] = bflo(nv[j].x); v[j][1] = bfhi(nv[j].x); v[j][2] = bflo(nv[j].y); v[j][3] = bfhi(nv[j].y); s += (v[j][0] + v[j][1]) + (v[j][2] + v[j][3]); }
;         if (rl + c.G * 8 < c.stok) { const bf16_t* hp = hr + (size_t)c.G * 8 * D;
; #pragma unroll
;             for (int j = 0; j < 4; ++j) nv[j] = *(const u32x2*)(hp + 4 * lane + 256 * j); }
.LBB0_1220:
	s_add_i32 s26, s26, s0
	s_cmp_ge_i32 s26, s41
	s_cselect_b64 s[22:23], -1, 0
	s_and_b64 vcc, exec, s[22:23]
	s_cbranch_vccnz .LBB0_1222
	s_add_u32 s24, s16, s20
	s_addc_u32 s25, s17, s21
	v_lshl_add_u64 v[188:189], s[24:25], 0, v[2:3]
	v_lshl_add_u64 v[46:47], s[16:17], 0, v[2:3]
	global_load_dwordx2 v[186:187], v[188:189], off
	global_load_dwordx2 v[186:187], v[188:189], off offset:512
	global_load_dwordx2 v[186:187], v[188:189], off offset:1024
	global_load_dwordx2 v[186:187], v[188:189], off offset:1536
	global_load_dwordx2 v[40:41], v[46:47], off
	global_load_dwordx2 v[42:43], v[46:47], off offset:512
	global_load_dwordx2 v[44:45], v[46:47], off offset:1024
	s_nop 0
	global_load_dwordx2 v[46:47], v[46:47], off offset:1536
	s_branch .LBB0_1223

; #define LAS __attribute__((address_space(3)))
; DI unsigned pk2(float lo, float hi) { f32x2 v = {lo, hi}; bf16x2v b = __builtin_convertvector(v, bf16x2v); return __builtin_bit_cast(unsigned, b); }
; DI float bflo(unsigned u) { return __uint_as_float(u << 16); }
; DI float bfhi(unsigned u) { return __uint_as_float(u & 0xffff0000u); }
; DI float frsq(float x) { return __builtin_amdgcn_rsqf(x); }
; DI void phase_ln1(KArgs args, LAS unsigned char* L, const Ctx& c) {
;     ...
;     for (int rl = c.bid * 8 + c.wave; rl < c.stok; rl += c.G * 8) { const size_t tok = (size_t)c.sbase + rl;
;         const bf16_t* hr = (const bf16_t*)c.out + tok * D; f32x4 v[4]; float s = 0.f;
; #pragma unroll
;         for (int j = 0; j < 4; ++j) { v[j][0] = bflo(nv[j].x); v[j][1] = bfhi(nv[j].x); v[j][2] = bflo(nv[j].y); v[j][3] = bfhi(nv[j].y); s += (v[j][0] + v[j][1]) + (v[j][2] + v[j][3]); }
;         if (rl + c.G * 8 < c.stok) { const bf16_t* hp = hr + (size_t)c.G * 8 * D;
; #pragma unroll
;             for (int j = 0; j < 4; ++j) nv[j] = *(const u32x2*)(hp + 4 * lane + 256 * j); }
;         const float mean = wave_sum(s) * (1.0f / D); float s2 = 0.f;
; #pragma unroll
;         for (int j = 0; j < 4; ++j) { v[j] = v[j] - mean; s2 += (v[j][0] * v[j][0] + v[j][1] * v[j][1]) + (v[j][2] * v[j][2] + v[j][3] * v[j][3]); }
;         const float rstd = frsq(wave_sum(s2) * (1.0f / D) + LN_EPS);
;         float lg[16];
; #pragma unroll
;         for (int e = 0; e < 16; ++e) lg[e] = 0.f;
; #pragma unroll
;         for (int j = 0; j < 4; ++j) { v[j] = v[j] * rstd * gv[j] + bv[j];
;             if (!c.dry) { u32x2 w; w.x = pk2(v[j][0], v[j][1]); w.y = pk2(v[j][2], v[j][3]); *(u32x2*)(XB + tok * D + 4 * lane + 256 * j) = w; }
; #pragma unroll
;             for (int q = 0; q < 4; ++q) { const LAS float* wp = WR + ((j * 4 + q) * 64 + lane) * 20; const float xv = v[j][q];
; #pragma unroll
;                 for (int e4 = 0; e4 < 4; ++e4) { const f32x4 w4 = *(const LAS f32x4*)(wp + 4 * e4); lg[4 * e4] += xv * w4[0]; lg[4 * e4 + 1] += xv * w4[1]; lg[4 * e4 + 2] += xv * w4[2]; lg[4 * e4 + 3] += xv * w4[3]; } }
;             asm volatile("" ::: "memory"); }
.LBB0_1223:
	ds_read_b128 v[114:117], v1 offset:0
	ds_read_b128 v[118:121], v1 offset:16
	ds_read_b128 v[122:125], v1 offset:32
	ds_read_b128 v[126:129], v1 offset:48
	ds_read_b128 v[130:133], v1 offset:5120
	ds_read_b128 v[134:137], v1 offset:5136
	ds_read_b128 v[138:141], v1 offset:5152
	ds_read_b128 v[142:145], v1 offset:5168
	s_waitcnt vmcnt(11)
	v_lshlrev_b32_e32 v82, 16, v54
	v_and_b32_e32 v83, 0xffff0000, v54
	v_lshlrev_b32_e32 v84, 16, v55
	v_and_b32_e32 v85, 0xffff0000, v55
	v_add_f32_e32 v54, v82, v83
	v_add_f32_e32 v55, v84, v85
	s_waitcnt vmcnt(10)
	v_lshlrev_b32_e32 v60, 16, v52
	v_and_b32_e32 v61, 0xffff0000, v52
	v_lshlrev_b32_e32 v62, 16, v53
	v_and_b32_e32 v63, 0xffff0000, v53
	v_add_f32_e32 v54, v54, v55
	v_add_f32_e32 v52, v60, v61
	v_add_f32_e32 v53, v62, v63
	s_waitcnt vmcnt(9)
	v_lshlrev_b32_e32 v56, 16, v50
	v_and_b32_e32 v57, 0xffff0000, v50
	v_lshlrev_b32_e32 v58, 16, v51
	v_and_b32_e32 v59, 0xffff0000, v51
	v_add_f32_e32 v54, 0, v54
	v_add_f32_e32 v52, v52, v53
	v_add_f32_e32 v50, v56, v57
	v_add_f32_e32 v51, v58, v59
	v_add_f32_e32 v52, v52, v54
	v_add_f32_e32 v50, v50, v51
	v_add_f32_e32 v54, v50, v52
	s_waitcnt vmcnt(8)
	v_lshlrev_b32_e32 v52, 16, v48
	v_and_b32_e32 v53, 0xffff0000, v48
	v_lshlrev_b32_e32 v50, 16, v49
	v_and_b32_e32 v51, 0xffff0000, v49
	v_add_f32_e32 v48, v52, v53
	v_add_f32_e32 v49, v50, v51
	v_add_f32_e32 v48, v48, v49
	v_add_f32_e32 v48, v48, v54
	s_nop 1
	v_add_f32_dpp v48, v48, v48 quad_perm:[1,0,3,2] row_mask:0xf bank_mask:0xf
	s_nop 1
	v_add_f32_dpp v48, v48, v48 quad_perm:[2,3,0,1] row_mask:0xf bank_mask:0xf
	s_nop 1
	v_add_f32_dpp v48, v48, v48 row_half_mirror row_mask:0xf bank_mask:0xf
	s_nop 1
	v_add_f32_dpp v48, v48, v48 row_mirror row_mask:0xf bank_mask:0xf
	s_nop 1
	v_add_f32_dpp v48, v48, v48 row_bcast:15 row_mask:0xa bank_mask:0xf
	s_nop 1
	v_add_f32_dpp v48, v48, v48 row_bcast:31 row_mask:0xc bank_mask:0xf
	s_nop 1
	v_readlane_b32 s28, v48, 63
	s_mov_b32 s1, 0x3fb8aa3b
	s_nop 0
	v_mov_b32_e32 v90, s28
	v_fmac_f32_e32 v83, 0xba800000, v90
	v_fmac_f32_e32 v82, 0xba800000, v90
	v_fmac_f32_e32 v85, 0xba800000, v90
	v_fmac_f32_e32 v84, 0xba800000, v90
	v_pk_mul_f32 v[48:49], v[84:85], v[84:85]
	v_pk_mul_f32 v[54:55], v[82:83], v[82:83]
	v_fmac_f32_e32 v61, 0xba800000, v90
	v_pk_mov_b32 v[86:87], v[54:55], v[48:49] op_sel:[1,0]
	v_mov_b32_e32 v55, v49
	v_pk_add_f32 v[48:49], v[86:87], v[54:55]
	v_fmac_f32_e32 v60, 0xba800000, v90
	v_fmac_f32_e32 v63, 0xba800000, v90
	v_fmac_f32_e32 v62, 0xba800000, v90
	v_pk_add_f32 v[48:49], v[48:49], v[48:49] op_sel_hi:[0,1]
	v_pk_mul_f32 v[54:55], v[62:63], v[62:63]
	v_pk_mul_f32 v[86:87], v[60:61], v[60:61]
	v_fmac_f32_e32 v56, 0xba800000, v90
	v_pk_mov_b32 v[88:89], v[86:87], v[54:55] op_sel:[1,0]
	v_mov_b32_e32 v87, v55
	v_fmac_f32_e32 v57, 0xba800000, v90
	v_fmac_f32_e32 v58, 0xba800000, v90
	v_mul_f32_e32 v48, v56, v56
	v_pk_add_f32 v[54:55], v[88:89], v[86:87]
	v_fmac_f32_e32 v59, 0xba800000, v90
	v_pk_fma_f32 v[86:87], v[56:57], v[56:57], v[48:49] op_sel_hi:[1,1,0]
	v_mul_f32_e32 v48, v58, v58
	v_pk_add_f32 v[54:55], v[54:55], v[54:55] op_sel_hi:[0,1]
	v_pk_fma_f32 v[88:89], v[58:59], v[58:59], v[48:49] op_sel_hi:[1,1,0]
	v_fmac_f32_e32 v51, 0xba800000, v90
	v_fmac_f32_e32 v50, 0xba800000, v90
	v_fmac_f32_e32 v53, 0xba800000, v90
	v_fmac_f32_e32 v52, 0xba800000, v90
	v_mul_f32_e32 v86, v52, v52
	v_mul_f32_e32 v88, v53, v53
	v_mul_f32_e32 v48, v50, v50
	v_mul_f32_e32 v54, v51, v51
	v_pk_add_f32 v[86:87], v[86:87], v[88:89]
	v_pk_add_f32 v[48:49], v[48:49], v[54:55]
	s_nop 0
	v_pk_add_f32 v[48:49], v[86:87], v[48:49]
	s_nop 0
	v_add_f32_e32 v48, v48, v49
	s_nop 1
	v_add_f32_dpp v48, v48, v48 quad_perm:[1,0,3,2] row_mask:0xf bank_mask:0xf
	s_nop 1
	v_add_f32_dpp v48, v48, v48 quad_perm:[2,3,0,1] row_mask:0xf bank_mask:0xf
	s_nop 1
	v_add_f32_dpp v48, v48, v48 row_half_mirror row_mask:0xf bank_mask:0xf
	s_nop 1
	v_add_f32_dpp v48, v48, v48 row_mirror row_mask:0xf bank_mask:0xf
	s_nop 1
	v_add_f32_dpp v48, v48, v48 row_bcast:15 row_mask:0xa bank_mask:0xf
	s_nop 1
	v_add_f32_dpp v48, v48, v48 row_bcast:31 row_mask:0xc bank_mask:0xf
	s_nop 1
	v_readlane_b32 s28, v48, 63
	s_nop 1
	v_mov_b32_e32 v48, s28
	v_fmamk_f32 v48, v48, 0x3a800000, v214
	v_rsq_f32_e32 v54, v48
	v_lshl_add_u64 v[48:49], s[18:19], 0, v[2:3]
	v_pk_mul_f32 v[82:83], v[82:83], v[54:55] op_sel_hi:[1,0]
	v_pk_mul_f32 v[84:85], v[84:85], v[54:55] op_sel_hi:[1,0]
	v_pk_fma_f32 v[110:111], v[32:33], v[82:83], v[24:25]
	v_pk_fma_f32 v[108:109], v[34:35], v[84:85], v[26:27]
	v_cvt_pk_bf16_f32 v86, v110, v111
	v_cvt_pk_bf16_f32 v87, v108, v109
	global_store_dwordx2 v[48:49], v[86:87], off offset:-1024
	s_waitcnt lgkmcnt(4)
	ds_read_b128 v[146:149], v1 offset:10240
	ds_read_b128 v[150:153], v1 offset:10256
	ds_read_b128 v[154:157], v1 offset:10272
	ds_read_b128 v[158:161], v1 offset:10288
	v_pk_mul_f32 v[162:163], v[114:115], v[110:111] op_sel_hi:[1,0]
	v_pk_mul_f32 v[164:165], v[116:117], v[110:111] op_sel_hi:[1,0]
	v_pk_mul_f32 v[166:167], v[118:119], v[110:111] op_sel_hi:[1,0]
	v_pk_mul_f32 v[168:169], v[120:121], v[110:111] op_sel_hi:[1,0]
	v_pk_mul_f32 v[170:171], v[122:123], v[110:111] op_sel_hi:[1,0]
	v_pk_mul_f32 v[172:173], v[124:125], v[110:111] op_sel_hi:[1,0]
	v_pk_mul_f32 v[174:175], v[126:127], v[110:111] op_sel_hi:[1,0]
	v_pk_mul_f32 v[176:177], v[128:129], v[110:111] op_sel_hi:[1,0]
	s_waitcnt lgkmcnt(4)
; #define LAS __attribute__((address_space(3)))
; DI unsigned pk2(float lo, float hi) { f32x2 v = {lo, hi}; bf16x2v b = __builtin_convertvector(v, bf16x2v); return __builtin_bit_cast(unsigned, b); }
; DI void phase_ln1(KArgs args, LAS unsigned char* L, const Ctx& c) {
;     ...
;         for (int j = 0; j < 4; ++j) { v[j] = v[j] * rstd * gv[j] + bv[j];
;             if (!c.dry) { u32x2 w; w.x = pk2(v[j][0], v[j][1]); w.y = pk2(v[j][2], v[j][3]); *(u32x2*)(XB + tok * D + 4 * lane + 256 * j) = w; }
; #pragma unroll
;             for (int q = 0; q < 4; ++q) { const LAS float* wp = WR + ((j * 4 + q) * 64 + lane) * 20; const float xv = v[j][q];
; #pragma unroll
;                 for (int e4 = 0; e4 < 4; ++e4) { const f32x4 w4 = *(const LAS f32x4*)(wp + 4 * e4); lg[4 * e4] += xv * w4[0]; lg[4 * e4 + 1] += xv * w4[1]; lg[4 * e4 + 2] += xv * w4[2]; lg[4 * e4 + 3] += xv * w4[3]; } }
	ds_read_b128 v[114:117], v1 offset:15360
	ds_read_b128 v[118:121], v1 offset:15376
	ds_read_b128 v[122:125], v1 offset:15392
	ds_read_b128 v[126:129], v1 offset:15408
	v_pk_fma_f32 v[162:163], v[130:131], v[110:111], v[162:163] op_sel:[0,1,0]
	v_pk_fma_f32 v[164:165], v[132:133], v[110:111], v[164:165] op_sel:[0,1,0]
	v_pk_fma_f32 v[166:167], v[134:135], v[110:111], v[166:167] op_sel:[0,1,0]
	v_pk_fma_f32 v[168:169], v[136:137], v[110:111], v[168:169] op_sel:[0,1,0]
	v_pk_fma_f32 v[170:171], v[138:139], v[110:111], v[170:171] op_sel:[0,1,0]
	v_pk_fma_f32 v[172:173], v[140:141], v[110:111], v[172:173] op_sel:[0,1,0]
	v_pk_fma_f32 v[174:175], v[142:143], v[110:111], v[174:175] op_sel:[0,1,0]
	v_pk_fma_f32 v[176:177], v[144:145], v[110:111], v[176:177] op_sel:[0,1,0]
	s_waitcnt lgkmcnt(4)
	ds_read_b128 v[130:133], v1 offset:20480
	ds_read_b128 v[134:137], v1 offset:20496
	ds_read_b128 v[138:141], v1 offset:20512
	ds_read_b128 v[142:145], v1 offset:20528
	v_pk_fma_f32 v[162:163], v[146:147], v[108:109], v[162:163] op_sel_hi:[1,0,1]
	v_pk_fma_f32 v[164:165], v[148:149], v[108:109], v[164:165] op_sel_hi:[1,0,1]
	v_pk_fma_f32 v[166:167], v[150:151], v[108:109], v[166:167] op_sel_hi:[1,0,1]
	v_pk_fma_f32 v[168:169], v[152:153], v[108:109], v[168:169] op_sel_hi:[1,0,1]
	v_pk_fma_f32 v[170:171], v[154:155], v[108:109], v[170:171] op_sel_hi:[1,0,1]
	v_pk_fma_f32 v[172:173], v[156:157], v[108:109], v[172:173] op_sel_hi:[1,0,1]
	v_pk_fma_f32 v[174:175], v[158:159], v[108:109], v[174:175] op_sel_hi:[1,0,1]
	v_pk_fma_f32 v[176:177], v[160:161], v[108:109], v[176:177] op_sel_hi:[1,0,1]
	s_waitcnt lgkmcnt(4)
	ds_read_b128 v[146:149], v1 offset:25600
	ds_read_b128 v[150:153], v1 offset:25616
	ds_read_b128 v[154:157], v1 offset:25632
	ds_read_b128 v[158:161], v1 offset:25648
	v_pk_fma_f32 v[162:163], v[114:115], v[108:109], v[162:163] op_sel:[0,1,0]
	v_pk_fma_f32 v[164:165], v[116:117], v[108:109], v[164:165] op_sel:[0,1,0]
	v_pk_fma_f32 v[166:167], v[118:119], v[108:109], v[166:167] op_sel:[0,1,0]
	v_pk_fma_f32 v[168:169], v[120:121], v[108:109], v[168:169] op_sel:[0,1,0]
	v_pk_fma_f32 v[170:171], v[122:123], v[108:109], v[170:171] op_sel:[0,1,0]
	v_pk_fma_f32 v[172:173], v[124:125], v[108:109], v[172:173] op_sel:[0,1,0]
	v_pk_fma_f32 v[174:175], v[126:127], v[108:109], v[174:175] op_sel:[0,1,0]
	v_pk_fma_f32 v[176:177], v[128:129], v[108:109], v[176:177] op_sel:[0,1,0]
	v_pk_mul_f32 v[60:61], v[60:61], v[54:55] op_sel_hi:[1,0]
	v_pk_mul_f32 v[62:63], v[62:63], v[54:55] op_sel_hi:[1,0]
	v_pk_fma_f32 v[112:113], v[28:29], v[60:61], v[20:21]
	v_pk_fma_f32 v[110:111], v[30:31], v[62:63], v[22:23]
	v_cvt_pk_bf16_f32 v88, v112, v113
	v_cvt_pk_bf16_f32 v89, v110, v111
	global_store_dwordx2 v[48:49], v[88:89], off offset:-512
	s_waitcnt lgkmcnt(4)
	ds_read_b128 v[114:117], v1 offset:30720
	ds_read_b128 v[118:121], v1 offset:30736
	ds_read_b128 v[122:125], v1 offset:30752
	ds_read_b128 v[126:129], v1 offset:30768
	v_pk_fma_f32 v[162:163], v[130:131], v[112:113], v[162:163] op_sel_hi:[1,0,1]
	v_pk_fma_f32 v[164:165], v[132:133], v[112:113], v[164:165] op_sel_hi:[1,0,1]
	v_pk_fma_f32 v[166:167], v[134:135], v[112:113], v[166:167] op_sel_hi:[1,0,1]
	v_pk_fma_f32 v[168:169], v[136:137], v[112:113], v[168:169] op_sel_hi:[1,0,1]
	v_pk_fma_f32 v[170:171], v[138:139], v[112:113], v[170:171] op_sel_hi:[1,0,1]
	v_pk_fma_f32 v[172:173], v[140:141], v[112:113], v[172:173] op_sel_hi:[1,0,1]
	v_pk_fma_f32 v[174:175], v[142:143], v[112:113], v[174:175] op_sel_hi:[1,0,1]
	v_pk_fma_f32 v[176:177], v[144:145], v[112:113], v[176:177] op_sel_hi:[1,0,1]
	s_waitcnt lgkmcnt(4)
	ds_read_b128 v[130:133], v1 offset:35840
	ds_read_b128 v[134:137], v1 offset:35856
	ds_read_b128 v[138:141], v1 offset:35872
	ds_read_b128 v[142:145], v1 offset:35888
	v_pk_fma_f32 v[162:163], v[146:147], v[112:113], v[162:163] op_sel:[0,1,0]
	v_pk_fma_f32 v[164:165], v[148:149], v[112:113], v[164:165] op_sel:[0,1,0]
	v_pk_fma_f32 v[166:167], v[150:151], v[112:113], v[166:167] op_sel:[0,1,0]
	v_pk_fma_f32 v[168:169], v[152:153], v[112:113], v[168:169] op_sel:[0,1,0]
	v_pk_fma_f32 v[170:171], v[154:155], v[112:113], v[170:171] op_sel:[0,1,0]
	v_pk_fma_f32 v[172:173], v[156:157], v[112:113], v[172:173] op_sel:[0,1,0]
	v_pk_fma_f32 v[174:175], v[158:159], v[112:113], v[174:175] op_sel:[0,1,0]
	v_pk_fma_f32 v[176:177], v[160:161], v[112:113], v[176:177] op_sel:[0,1,0]
	s_waitcnt lgkmcnt(4)
	ds_read_b128 v[146:149], v1 offset:40960
	ds_read_b128 v[150:153], v1 offset:40976
	ds_read_b128 v[154:157], v1 offset:40992
	ds_read_b128 v[158:161], v1 offset:41008
	v_pk_fma_f32 v[162:163], v[114:115], v[110:111], v[162:163] op_sel_hi:[1,0,1]
	v_pk_fma_f32 v[164:165], v[116:117], v[110:111], v[164:165] op_sel_hi:[1,0,1]
	v_pk_fma_f32 v[166:167], v[118:119], v[110:111], v[166:167] op_sel_hi:[1,0,1]
	v_pk_fma_f32 v[168:169], v[120:121], v[110:111], v[168:169] op_sel_hi:[1,0,1]
	v_pk_fma_f32 v[170:171], v[122:123], v[110:111], v[170:171] op_sel_hi:[1,0,1]
	v_pk_fma_f32 v[172:173], v[124:125], v[110:111], v[172:173] op_sel_hi:[1,0,1]
	v_pk_fma_f32 v[174:175], v[126:127], v[110:111], v[174:175] op_sel_hi:[1,0,1]
	v_pk_fma_f32 v[176:177], v[128:129], v[110:111], v[176:177] op_sel_hi:[1,0,1]
	s_waitcnt lgkmcnt(4)
; #define LAS __attribute__((address_space(3)))
; DI unsigned pk2(float lo, float hi) { f32x2 v = {lo, hi}; bf16x2v b = __builtin_convertvector(v, bf16x2v); return __builtin_bit_cast(unsigned, b); }
; DI void phase_ln1(KArgs args, LAS unsigned char* L, const Ctx& c) {
;     ...
;         for (int j = 0; j < 4; ++j) { v[j] = v[j] * rstd * gv[j] + bv[j];
;             if (!c.dry) { u32x2 w; w.x = pk2(v[j][0], v[j][1]); w.y = pk2(v[j][2], v[j][3]); *(u32x2*)(XB + tok * D + 4 * lane + 256 * j) = w; }
; #pragma unroll
;             for (int q = 0; q < 4; ++q) { const LAS float* wp = WR + ((j * 4 + q) * 64 + lane) * 20; const float xv = v[j][q];
; #pragma unroll
;                 for (int e4 = 0; e4 < 4; ++e4) { const f32x4 w4 = *(const LAS f32x4*)(wp + 4 * e4); lg[4 * e4] += xv * w4[0]; lg[4 * e4 + 1] += xv * w4[1]; lg[4 * e4 + 2] += xv * w4[2]; lg[4 * e4 + 3] += xv * w4[3]; } }
	ds_read_b128 v[114:117], v1 offset:46080
	ds_read_b128 v[118:121], v1 offset:46096
	ds_read_b128 v[122:125], v1 offset:46112
	ds_read_b128 v[126:129], v1 offset:46128
	v_pk_fma_f32 v[162:163], v[130:131], v[110:111], v[162:163] op_sel:[0,1,0]
	v_pk_fma_f32 v[164:165], v[132:133], v[110:111], v[164:165] op_sel:[0,1,0]
	v_pk_fma_f32 v[166:167], v[134:135], v[110:111], v[166:167] op_sel:[0,1,0]
	v_pk_fma_f32 v[168:169], v[136:137], v[110:111], v[168:169] op_sel:[0,1,0]
	v_pk_fma_f32 v[170:171], v[138:139], v[110:111], v[170:171] op_sel:[0,1,0]
	v_pk_fma_f32 v[172:173], v[140:141], v[110:111], v[172:173] op_sel:[0,1,0]
	v_pk_fma_f32 v[174:175], v[142:143], v[110:111], v[174:175] op_sel:[0,1,0]
	v_pk_fma_f32 v[176:177], v[144:145], v[110:111], v[176:177] op_sel:[0,1,0]
	v_pk_mul_f32 v[56:57], v[56:57], v[54:55] op_sel_hi:[1,0]
	v_pk_mul_f32 v[58:59], v[58:59], v[54:55] op_sel_hi:[1,0]
	v_pk_fma_f32 v[108:109], v[16:17], v[56:57], v[8:9]
	v_pk_fma_f32 v[106:107], v[18:19], v[58:59], v[10:11]
	v_cvt_pk_bf16_f32 v98, v108, v109
	v_cvt_pk_bf16_f32 v99, v106, v107
	global_store_dwordx2 v[48:49], v[98:99], off
	s_waitcnt lgkmcnt(4)
	ds_read_b128 v[130:133], v1 offset:51200
	ds_read_b128 v[134:137], v1 offset:51216
	ds_read_b128 v[138:141], v1 offset:51232
	ds_read_b128 v[142:145], v1 offset:51248
	v_pk_fma_f32 v[162:163], v[146:147], v[108:109], v[162:163] op_sel_hi:[1,0,1]
	v_pk_fma_f32 v[164:165], v[148:149], v[108:109], v[164:165] op_sel_hi:[1,0,1]
	v_pk_fma_f32 v[166:167], v[150:151], v[108:109], v[166:167] op_sel_hi:[1,0,1]
	v_pk_fma_f32 v[168:169], v[152:153], v[108:109], v[168:169] op_sel_hi:[1,0,1]
	v_pk_fma_f32 v[170:171], v[154:155], v[108:109], v[170:171] op_sel_hi:[1,0,1]
	v_pk_fma_f32 v[172:173], v[156:157], v[108:109], v[172:173] op_sel_hi:[1,0,1]
	v_pk_fma_f32 v[174:175], v[158:159], v[108:109], v[174:175] op_sel_hi:[1,0,1]
	v_pk_fma_f32 v[176:177], v[160:161], v[108:109], v[176:177] op_sel_hi:[1,0,1]
	s_waitcnt lgkmcnt(4)
	ds_read_b128 v[146:149], v1 offset:56320
	ds_read_b128 v[150:153], v1 offset:56336
	ds_read_b128 v[154:157], v1 offset:56352
	ds_read_b128 v[158:161], v1 offset:56368
	v_pk_fma_f32 v[162:163], v[114:115], v[108:109], v[162:163] op_sel:[0,1,0]
	v_pk_fma_f32 v[164:165], v[116:117], v[108:109], v[164:165] op_sel:[0,1,0]
	v_pk_fma_f32 v[166:167], v[118:119], v[108:109], v[166:167] op_sel:[0,1,0]
	v_pk_fma_f32 v[168:169], v[120:121], v[108:109], v[168:169] op_sel:[0,1,0]
	v_pk_fma_f32 v[170:171], v[122:123], v[108:109], v[170:171] op_sel:[0,1,0]
	v_pk_fma_f32 v[172:173], v[124:125], v[108:109], v[172:173] op_sel:[0,1,0]
	v_pk_fma_f32 v[174:175], v[126:127], v[108:109], v[174:175] op_sel:[0,1,0]
	v_pk_fma_f32 v[176:177], v[128:129], v[108:109], v[176:177] op_sel:[0,1,0]
	s_waitcnt lgkmcnt(4)
	ds_read_b128 v[114:117], v1 offset:61440
	ds_read_b128 v[118:121], v1 offset:61456
	ds_read_b128 v[122:125], v1 offset:61472
	ds_read_b128 v[126:129], v1 offset:61488
	v_pk_fma_f32 v[162:163], v[130:131], v[106:107], v[162:163] op_sel_hi:[1,0,1]
	v_pk_fma_f32 v[164:165], v[132:133], v[106:107], v[164:165] op_sel_hi:[1,0,1]
	v_pk_fma_f32 v[166:167], v[134:135], v[106:107], v[166:167] op_sel_hi:[1,0,1]
	v_pk_fma_f32 v[168:169], v[136:137], v[106:107], v[168:169] op_sel_hi:[1,0,1]
	v_pk_fma_f32 v[170:171], v[138:139], v[106:107], v[170:171] op_sel_hi:[1,0,1]
	v_pk_fma_f32 v[172:173], v[140:141], v[106:107], v[172:173] op_sel_hi:[1,0,1]
	v_pk_fma_f32 v[174:175], v[142:143], v[106:107], v[174:175] op_sel_hi:[1,0,1]
	v_pk_fma_f32 v[176:177], v[144:145], v[106:107], v[176:177] op_sel_hi:[1,0,1]
	s_waitcnt lgkmcnt(4)
	ds_read_b128 v[130:133], v64
	ds_read_b128 v[134:137], v65
	ds_read_b128 v[138:141], v66
	ds_read_b128 v[142:145], v67
	v_pk_fma_f32 v[162:163], v[146:147], v[106:107], v[162:163] op_sel:[0,1,0]
	v_pk_fma_f32 v[164:165], v[148:149], v[106:107], v[164:165] op_sel:[0,1,0]
	v_pk_fma_f32 v[166:167], v[150:151], v[106:107], v[166:167] op_sel:[0,1,0]
	v_pk_fma_f32 v[168:169], v[152:153], v[106:107], v[168:169] op_sel:[0,1,0]
	v_pk_fma_f32 v[170:171], v[154:155], v[106:107], v[170:171] op_sel:[0,1,0]
	v_pk_fma_f32 v[172:173], v[156:157], v[106:107], v[172:173] op_sel:[0,1,0]
	v_pk_fma_f32 v[174:175], v[158:159], v[106:107], v[174:175] op_sel:[0,1,0]
	v_pk_fma_f32 v[176:177], v[160:161], v[106:107], v[176:177] op_sel:[0,1,0]
	v_pk_mul_f32 v[52:53], v[52:53], v[54:55] op_sel_hi:[1,0]
	v_pk_mul_f32 v[50:51], v[50:51], v[54:55] op_sel_hi:[1,0]
	v_pk_fma_f32 v[52:53], v[12:13], v[52:53], v[4:5]
	v_pk_fma_f32 v[50:51], v[14:15], v[50:51], v[6:7]
	v_cvt_pk_bf16_f32 v100, v52, v53
	v_cvt_pk_bf16_f32 v101, v50, v51
	global_store_dwordx2 v[48:49], v[100:101], off offset:512
	s_waitcnt lgkmcnt(4)
	ds_read_b128 v[146:149], v68
	ds_read_b128 v[150:153], v69
	ds_read_b128 v[154:157], v70
	ds_read_b128 v[158:161], v71
	v_pk_fma_f32 v[162:163], v[114:115], v[52:53], v[162:163] op_sel_hi:[1,0,1]
	v_pk_fma_f32 v[164:165], v[116:117], v[52:53], v[164:165] op_sel_hi:[1,0,1]
	v_pk_fma_f32 v[166:167], v[118:119], v[52:53], v[166:167] op_sel_hi:[1,0,1]
	v_pk_fma_f32 v[168:169], v[120:121], v[52:53], v[168:169] op_sel_hi:[1,0,1]
	v_pk_fma_f32 v[170:171], v[122:123], v[52:53], v[170:171] op_sel_hi:[1,0,1]
	v_pk_fma_f32 v[172:173], v[124:125], v[52:53], v[172:173] op_sel_hi:[1,0,1]
	v_pk_fma_f32 v[174:175], v[126:127], v[52:53], v[174:175] op_sel_hi:[1,0,1]
	v_pk_fma_f32 v[176:177], v[128:129], v[52:53], v[176:177] op_sel_hi:[1,0,1]
	s_waitcnt lgkmcnt(4)
; DI void phase_ln1(KArgs args, LAS unsigned char* L, const Ctx& c) {
;     ...
;         const bool h5 = (lane & 32) != 0, h4 = (lane & 16) != 0, h3 = (lane & 8) != 0, h2 = (lane & 4) != 0;
;         const int eid = (h5 ? 8 : 0) + (h4 ? 4 : 0) + (h3 ? 2 : 0) + (h2 ? 1 : 0);
;         float a8[8], b4[4], c2[2], d;
; #pragma unroll
;         for (int k = 0; k < 8; ++k) { const float snd = h5 ? lg[k] : lg[k + 8]; a8[k] = (h5 ? lg[k + 8] : lg[k]) + __shfl_xor(snd, 32); }
; #pragma unroll
;         for (int k = 0; k < 4; ++k) { const float snd = h4 ? a8[k] : a8[k + 4]; b4[k] = (h4 ? a8[k + 4] : a8[k]) + __shfl_xor(snd, 16); }
; #pragma unroll
;         for (int k = 0; k < 2; ++k) { const float snd = h3 ? b4[k] : b4[k + 2]; c2[k] = (h3 ? b4[k + 2] : b4[k]) + __shfl_xor(snd, 8); }
;         { const float snd = h2 ? c2[0] : c2[1]; d = (h2 ? c2[1] : c2[0]) + __shfl_xor(snd, 4); }
;         d += __shfl_xor(d, 2); d += __shfl_xor(d, 1);
;         float mx = d;
;         mx = fmaxf(mx, __shfl_xor(mx, 32)); mx = fmaxf(mx, __shfl_xor(mx, 16)); mx = fmaxf(mx, __shfl_xor(mx, 8)); mx = fmaxf(mx, __shfl_xor(mx, 4));
;         const float pe = expf(d - mx); float den = pe;
;         den += __shfl_xor(den, 32); den += __shfl_xor(den, 16); den += __shfl_xor(den, 8); den += __shfl_xor(den, 4);
;         if ((lane & 3) == 0 && !c.dry) { AFF[(size_t)eid * T_ALL + tok] = pe / den; SLOT[tok * 16 + eid] = -1; }
	ds_read_b128 v[114:117], v72
	ds_read_b128 v[118:121], v73
	ds_read_b128 v[122:125], v74
	ds_read_b128 v[126:129], v75
	v_pk_fma_f32 v[162:163], v[130:131], v[52:53], v[162:163] op_sel:[0,1,0]
	v_pk_fma_f32 v[164:165], v[132:133], v[52:53], v[164:165] op_sel:[0,1,0]
	v_pk_fma_f32 v[166:167], v[134:135], v[52:53], v[166:167] op_sel:[0,1,0]
	v_pk_fma_f32 v[168:169], v[136:137], v[52:53], v[168:169] op_sel:[0,1,0]
	v_pk_fma_f32 v[170:171], v[138:139], v[52:53], v[170:171] op_sel:[0,1,0]
	v_pk_fma_f32 v[172:173], v[140:141], v[52:53], v[172:173] op_sel:[0,1,0]
	v_pk_fma_f32 v[174:175], v[142:143], v[52:53], v[174:175] op_sel:[0,1,0]
	v_pk_fma_f32 v[176:177], v[144:145], v[52:53], v[176:177] op_sel:[0,1,0]
	s_waitcnt lgkmcnt(4)
	v_pk_fma_f32 v[162:163], v[146:147], v[50:51], v[162:163] op_sel_hi:[1,0,1]
	v_pk_fma_f32 v[164:165], v[148:149], v[50:51], v[164:165] op_sel_hi:[1,0,1]
	v_pk_fma_f32 v[166:167], v[150:151], v[50:51], v[166:167] op_sel_hi:[1,0,1]
	v_pk_fma_f32 v[168:169], v[152:153], v[50:51], v[168:169] op_sel_hi:[1,0,1]
	v_pk_fma_f32 v[170:171], v[154:155], v[50:51], v[170:171] op_sel_hi:[1,0,1]
	v_pk_fma_f32 v[172:173], v[156:157], v[50:51], v[172:173] op_sel_hi:[1,0,1]
	v_pk_fma_f32 v[174:175], v[158:159], v[50:51], v[174:175] op_sel_hi:[1,0,1]
	v_pk_fma_f32 v[176:177], v[160:161], v[50:51], v[176:177] op_sel_hi:[1,0,1]
	s_waitcnt lgkmcnt(0)
	v_pk_fma_f32 v[162:163], v[114:115], v[50:51], v[162:163] op_sel:[0,1,0]
	v_pk_fma_f32 v[164:165], v[116:117], v[50:51], v[164:165] op_sel:[0,1,0]
	v_pk_fma_f32 v[166:167], v[118:119], v[50:51], v[166:167] op_sel:[0,1,0]
	v_pk_fma_f32 v[168:169], v[120:121], v[50:51], v[168:169] op_sel:[0,1,0]
	v_pk_fma_f32 v[170:171], v[122:123], v[50:51], v[170:171] op_sel:[0,1,0]
	v_pk_fma_f32 v[172:173], v[124:125], v[50:51], v[172:173] op_sel:[0,1,0]
	v_pk_fma_f32 v[174:175], v[126:127], v[50:51], v[174:175] op_sel:[0,1,0]
	v_pk_fma_f32 v[176:177], v[128:129], v[50:51], v[176:177] op_sel:[0,1,0]
	v_permlane32_swap_b32_e32 v162, v170
	v_permlane32_swap_b32_e32 v163, v171
	v_permlane32_swap_b32_e32 v164, v172
	v_permlane32_swap_b32_e32 v165, v173
	v_permlane32_swap_b32_e32 v166, v174
	v_permlane32_swap_b32_e32 v167, v175
	v_permlane32_swap_b32_e32 v168, v176
	v_permlane32_swap_b32_e32 v169, v177
	v_add_f32_e32 v162, v162, v170
	v_add_f32_e32 v163, v163, v171
	v_add_f32_e32 v164, v164, v172
	v_add_f32_e32 v165, v165, v173
	v_add_f32_e32 v166, v166, v174
	v_add_f32_e32 v167, v167, v175
	v_add_f32_e32 v168, v168, v176
	v_add_f32_e32 v169, v169, v177
	v_permlane16_swap_b32_e32 v162, v166
	v_permlane16_swap_b32_e32 v163, v167
	v_permlane16_swap_b32_e32 v164, v168
	v_permlane16_swap_b32_e32 v165, v169
	v_add_f32_e32 v162, v162, v166
	v_add_f32_e32 v163, v163, v167
	v_add_f32_e32 v164, v164, v168
	v_add_f32_e32 v165, v165, v169
	s_nop 1
	v_add_f32_dpp v178, v162, v162 row_ror:8 row_mask:0xf bank_mask:0x3
	v_add_f32_dpp v179, v163, v163 row_ror:8 row_mask:0xf bank_mask:0x3
	v_add_f32_dpp v178, v164, v164 row_ror:8 row_mask:0xf bank_mask:0xc
	v_add_f32_dpp v179, v165, v165 row_ror:8 row_mask:0xf bank_mask:0xc
	s_nop 1
	v_add_f32_dpp v180, v178, v178 row_shl:4 row_mask:0xf bank_mask:0x5
	v_add_f32_dpp v180, v179, v179 row_shr:4 row_mask:0xf bank_mask:0xa
	s_nop 1
	v_add_f32_dpp v180, v180, v180 quad_perm:[2,3,0,1] row_mask:0xf bank_mask:0xf
	s_nop 1
	v_add_f32_dpp v180, v180, v180 quad_perm:[1,0,3,2] row_mask:0xf bank_mask:0xf
	s_nop 1
	v_max_f32_dpp v181, v180, v180 row_ror:4 row_mask:0xf bank_mask:0xf
	s_nop 1
	v_max_f32_dpp v181, v181, v181 row_ror:8 row_mask:0xf bank_mask:0xf
	s_nop 0
	v_mov_b32_e32 v182, v181
	s_nop 1
	v_permlane16_swap_b32_e32 v181, v182
	v_max_f32_e32 v181, v181, v182
	v_mov_b32_e32 v182, v181
	s_nop 1
	v_permlane32_swap_b32_e32 v181, v182
	v_max_f32_e32 v55, v181, v182
	v_sub_f32_e32 v54, v180, v55
	v_mul_f32_e32 v55, 0x3fb8aa3b, v54
	v_fma_f32 v56, v54, s1, -v55
	v_rndne_f32_e32 v57, v55
	v_fmac_f32_e32 v56, 0x32a5705f, v54
	v_sub_f32_e32 v55, v55, v57
	v_add_f32_e32 v55, v55, v56
	v_exp_f32_e32 v55, v55
	v_cvt_i32_f32_e32 v56, v57
	s_mov_b32 s1, 0xc2ce8ed0
	v_cmp_ngt_f32_e32 vcc, s1, v54
	s_mov_b32 s1, 0x42b17218
	v_ldexp_f32 v55, v55, v56
	v_cndmask_b32_e32 v55, 0, v55, vcc
	v_cmp_nlt_f32_e32 vcc, s1, v54
	s_nop 1
	v_cndmask_b32_e32 v54, v213, v55, vcc
	v_mov_b32_e32 v184, v54
	v_mov_b32_e32 v185, v54
	s_nop 1
	v_permlane32_swap_b32_e32 v184, v185
	v_add_f32_e32 v184, v184, v185
	v_mov_b32_e32 v185, v184
	s_nop 1
	v_permlane16_swap_b32_e32 v184, v185
	v_add_f32_e32 v184, v184, v185
	s_nop 1
	v_add_f32_dpp v184, v184, v184 row_ror:8 row_mask:0xf bank_mask:0xf
	s_nop 1
	v_add_f32_dpp v48, v184, v184 row_ror:4 row_mask:0xf bank_mask:0xf
	s_and_saveexec_b64 s[24:25], s[12:13]
	s_cbranch_execz .LBB0_1219
	v_div_scale_f32 v49, s[28:29], v48, v48, v54
	v_rcp_f32_e32 v50, v49
	v_div_scale_f32 v51, vcc, v54, v48, v54
	v_fma_f32 v52, -v49, v50, 1.0
	v_fmac_f32_e32 v50, v52, v50
	v_mul_f32_e32 v52, v51, v50
	v_fma_f32 v53, -v49, v52, v51
	v_fmac_f32_e32 v52, v53, v50
	v_fma_f32 v49, -v49, v52, v51
	v_div_fmas_f32 v49, v49, v50, v52
	v_div_fixup_f32 v48, v49, v48, v54
	global_store_dword v[36:37], v48, off
	v_mov_b32_e32 v48, -1
	global_store_dword v[38:39], v48, off
	s_branch .LBB0_1219
